# mirror: flips deleted, static s_setprio 1 for waves 0-3 instead of 4-7
# baseline (speedup 1.0000x reference)
; DI int opq_tid() { int t = threadIdx.x; asm volatile("" : "+v"(t)); return t; }
; #define PG8_STAGE(bufoff, gbase, voff) do { _Pragma("unroll") for (int _i = 0; _i < 2; ++_i) \
;         __builtin_amdgcn_global_load_lds((const unsigned*)((const char*)(gbase) + (voff)[_i]), (LAS unsigned*)(lds + (bufoff) + ldsw + _i * 8192), 16, 0, 0); } while (0)
; #define PG8_BAR __builtin_amdgcn_s_barrier()
; DI void gemm_phase(LAS unsigned char* lds, const Sched& S, const Epi& Ep) {
;     const int tid = opq_tid(), wid = __builtin_amdgcn_readfirstlane(tid >> 6), lane = tid & 63, wr = wid >> 2, wc = wid & 3, fr = lane & 15, fq = lane >> 4;
;     const int K = S.K, nt = K / BK;
;     unsigned voffA[2], voffB[2];
; #pragma unroll
;     for (int i = 0; i < 2; ++i) { int R, C; stage_rc(tid * 16 + i * 8192, R, C); const int Rb = Ep.PERM ? ((R & ~31) + perm32(R & 31)) : R;
;         voffA[i] = (unsigned)(R * S.lda + C) * 2u; voffB[i] = (unsigned)(Rb * S.ldb + C) * 2u; }
;     const size_t kstep = (size_t)(BK * 2);
;     const size_t hstepA = (size_t)HALF * S.lda * 2, hstepB = (size_t)HALF * S.ldb * 2;
;     const unsigned ldsw = (unsigned)wid * 1024u;
;     const int aoff = lds_byte(wr * 64 + fr, fq * 8), boff = lds_byte(wc * 32 + fr, fq * 8);
;     ...
;     Unit cur, nxt; int ui = 0;
;     if (!S.next(0, cur)) return;
;     f32x4 acc[2][2][4][2];
; #pragma unroll
;     for (int a = 0; a < 2; ++a)
; #pragma unroll
;         for (int b = 0; b < 2; ++b)
; #pragma unroll
;             for (int m = 0; m < 4; ++m)
; #pragma unroll
;                 for (int n = 0; n < 2; ++n) acc[a][b][m][n] = (f32x4){0.f, 0.f, 0.f, 0.f};
;     bf16x8 At[4][2], B0[2][2], B1[2][2];
;     const char* cA = S.pa(cur); const char* cB = S.pb(cur);
;     PG8_STAGE(PG8_SB(0, 0), cB, voffB); PG8_STAGE(PG8_SB(0, 1), cB + hstepB, voffB); PG8_STAGE(PG8_SA(0, 0), cA, voffA); PG8_STAGE(PG8_SA(0, 1), cA + hstepA, voffA);
;     if (wr == 1) PG8_BAR;
.LBB0_331:
	v_bfe_i32 v4, v0, 27, 1
	v_lshlrev_b32_e32 v2, 4, v0
	v_lshrrev_b32_e32 v4, 22, v4
	v_add_u32_e32 v4, v2, v4
	v_and_b32_e32 v4, 0xfffffc00, v4
	v_ashrrev_i32_e32 v3, 31, v0
	v_sub_u32_e32 v4, v2, v4
	v_lshrrev_b32_e32 v3, 26, v3
	v_lshrrev_b32_e32 v5, 4, v4
	v_add_u32_e32 v3, v0, v3
	v_bitop3_b32 v5, v5, v4, 32 bitop3:0x6c
	v_ashrrev_i32_e32 v4, 31, v4
	v_ashrrev_i32_e32 v3, 6, v3
	v_lshrrev_b32_e32 v4, 26, v4
	v_lshlrev_b32_e32 v6, 3, v3
	v_add_u32_e32 v4, v5, v4
	v_and_b32_e32 v6, -16, v6
	v_ashrrev_i32_e32 v4, 6, v4
	v_lshlrev_b32_e32 v3, 5, v3
	v_add_u32_e32 v6, v4, v6
	v_and_b32_e32 v14, 32, v3
	v_mul_i32_i24_e32 v3, 64, v4
	v_sub_u32_e32 v3, v5, v3
	v_mov_b32_e32 v8, 1
	v_lshlrev_b32_e32 v5, 1, v6
	v_lshrrev_b32_e32 v7, 2, v6
	v_and_b32_e32 v4, 3, v4
	s_movk_i32 s10, 0xffe0
	v_ashrrev_i16_sdwa v3, v8, sext(v3) dst_sel:DWORD dst_unused:UNUSED_PAD src0_sel:DWORD src1_sel:BYTE_0
	v_and_b32_e32 v5, 24, v5
	v_and_b32_e32 v7, 4, v7
	v_and_or_b32 v4, v6, s10, v4
	v_bfe_i32 v15, v3, 0, 16
	v_or3_b32 v4, v4, v7, v5
	v_add_u32_e32 v3, v14, v15
	v_mul_lo_u32 v16, v6, s53
	v_mul_lo_u32 v4, v4, s52
	v_add_u32_e32 v2, 0x2000, v2
	v_add_lshl_u32 v194, v3, v16, 1
	v_add_lshl_u32 v196, v4, v3, 1
	v_ashrrev_i32_e32 v3, 31, v2
	v_lshrrev_b32_e32 v3, 22, v3
	v_add_u32_e32 v3, v2, v3
	v_ashrrev_i32_e32 v3, 10, v3
	v_mul_i32_i24_e32 v4, 0x400, v3
	v_sub_u32_e32 v2, v2, v4
	v_lshrrev_b32_e32 v4, 4, v2
	v_bitop3_b32 v2, v4, v2, 32 bitop3:0x6c
	v_ashrrev_i32_e32 v5, 31, v2
	v_lshrrev_b32_e32 v5, 26, v5
	v_lshlrev_b32_e32 v4, 3, v3
	v_add_u32_e32 v5, v2, v5
	v_and_b32_e32 v4, -16, v4
	v_ashrrev_i32_e32 v6, 6, v5
	v_lshlrev_b32_e32 v3, 5, v3
	s_ashr_i32 s3, s8, 6
	v_add_u32_e32 v4, v6, v4
	v_and_b32_e32 v17, 32, v3
	v_and_b32_e32 v3, 0xc0, v5
	v_sub_u32_e32 v2, v2, v3
	v_lshlrev_b32_e32 v3, 1, v4
	v_lshrrev_b32_e32 v5, 2, v4
	v_and_b32_e32 v6, 3, v6
	s_lshl_b32 s19, s3, 10
	v_ashrrev_i16_sdwa v2, v8, sext(v2) dst_sel:DWORD dst_unused:UNUSED_PAD src0_sel:DWORD src1_sel:BYTE_0
	v_and_b32_e32 v3, 24, v3
	v_and_b32_e32 v5, 4, v5
	v_and_or_b32 v6, v4, s10, v6
	s_add_i32 s96, s19, 0
	v_bfe_i32 v18, v2, 0, 16
	v_or3_b32 v3, v6, v5, v3
	s_add_i32 m0, s96, 0x10000
	v_add_u32_e32 v2, v17, v18
	v_mul_lo_u32 v3, v3, s52
	s_ashr_i32 s15, s8, 8
	global_load_lds_dwordx4 v196, s[44:45]
	s_add_i32 m0, s96, 0x12000
	v_add_lshl_u32 v200, v3, v2, 1
	s_add_u32 s12, s44, s77
	global_load_lds_dwordx4 v200, s[44:45]
	s_addc_u32 s13, s45, 0
	s_add_i32 m0, s96, 0x14000
	v_mov_b32_e32 v197, v1
	v_mov_b32_e32 v201, v1
	global_load_lds_dwordx4 v196, s[12:13]
	s_add_i32 m0, s96, 0x16000
	s_add_i32 s90, s96, 0x2000
	v_mul_lo_u32 v19, v4, s53
	v_lshl_add_u64 v[6:7], s[12:13], 0, v[196:197]
	v_lshl_add_u64 v[8:9], s[12:13], 0, v[200:201]
	global_load_lds_dwordx4 v200, s[12:13]
	s_mov_b32 m0, s96
	s_add_u32 s12, s46, s6
	v_add_lshl_u32 v198, v2, v19, 1
	global_load_lds_dwordx4 v194, s[46:47]
	s_mov_b32 m0, s90
	s_addc_u32 s13, s47, 0
	s_add_i32 s91, s96, 0x4000
	global_load_lds_dwordx4 v198, s[46:47]
	s_mov_b32 m0, s91
	s_add_i32 s28, s96, 0x6000
	global_load_lds_dwordx4 v194, s[12:13]
	s_mov_b32 m0, s28
	v_writelane_b32 v255, s62, 26
	global_load_lds_dwordx4 v198, s[12:13]
	s_nop 0
	v_writelane_b32 v255, s63, 27
	v_writelane_b32 v255, s60, 28
	v_mov_b32_e32 v195, v1
	v_mov_b32_e32 v199, v1
	v_writelane_b32 v255, s61, 29
	v_writelane_b32 v255, s30, 30
	s_cmp_eq_u32 s15, 1
	v_lshl_add_u64 v[2:3], s[44:45], 0, v[196:197]
	v_writelane_b32 v255, s31, 31
	v_writelane_b32 v255, s58, 32
	v_lshl_add_u64 v[4:5], s[44:45], 0, v[200:201]
	v_lshl_add_u64 v[10:11], s[46:47], 0, v[194:195]
	v_writelane_b32 v255, s59, 33
	v_writelane_b32 v255, s56, 34
	v_lshl_add_u64 v[12:13], s[46:47], 0, v[198:199]
	s_cselect_b64 s[16:17], -1, 0
	v_writelane_b32 v255, s57, 35
	s_setprio 1
	s_cmp_lg_u32 s15, 1
	s_cbranch_scc1 .LBB0_333
	s_barrier
	s_setprio 0
